# grid barrier: the L1 invalidate is issued by wave 1 of each workgroup right after the workgroup barrier, concurrently with wave 0 running the arrival protocol
# speedup vs baseline: 1.0032x; 1.0032x over previous
; __device__ __forceinline__ unsigned xb_ld(unsigned* p)              { return __hip_atomic_load(p, __ATOMIC_RELAXED, __HIP_MEMORY_SCOPE_AGENT); }
; __device__ __forceinline__ void xcd_barrier_complete(unsigned* bar, unsigned x, unsigned& nloc, unsigned& nx) {
;     const unsigned G = gridDim.x * gridDim.y * gridDim.z;
;     unsigned sum, cnt, mine, sp = 0u;
;     for (;;) {
;         sum = 0u; cnt = 0u; mine = 0u;
; #pragma unroll
;         for (unsigned j = 0; j < 16; ++j) { const unsigned c = xb_ld(&bar[XB_XCNT(j)]); sum += c; cnt += (c > 0u) ? 1u : 0u; mine = (j == x) ? c : mine; }
;         if (sum == G) break;
;         __builtin_amdgcn_s_sleep(1);
;         if ((++sp & 255u) == 0u) { if (xb_ld(&bar[XB_TMO])) break; if (sp > XB_SPIN_CAP) { atomicAdd(&bar[XB_TMO], 1u); break; } }
;     }
;     nloc = mine > 0u ? mine : 1u; nx = cnt > 0u ? cnt : 1u;
; }
; __device__ __forceinline__ void xcd_barrier(const XcdBarrier& b) {
;     asm volatile("s_waitcnt vmcnt(0)" ::: "memory");
;     __syncthreads();
;     if (threadIdx.x == 0) {
;         unsigned* bar = b.bar;
;         __builtin_amdgcn_s_waitcnt(0);
;         unsigned nloc = b.st[0], nx = b.st[1];
;         if (nloc == 0u) { xcd_barrier_complete(bar, b.x, nloc, nx); b.st[0] = nloc; b.st[1] = nx; }
.LBB0_84:
	s_or_b64 exec, exec, s[16:17]
	s_mul_i32 s2, s67, s66
	s_mul_i32 s72, s2, s25
	s_add_u32 s2, s8, 0x35cc0200
	s_addc_u32 s3, s9, 0
	s_add_u32 s74, s8, 0x35cc0400
	s_addc_u32 s75, s9, 0
	s_add_u32 s76, s8, 0x35cc0500
	v_writelane_b32 v254, s2, 3
	s_addc_u32 s77, s9, 0
	s_waitcnt vmcnt(0)
	s_waitcnt lgkmcnt(0)
	v_writelane_b32 v254, s3, 4
	s_add_u32 s2, s8, 0x35cc0600
	s_addc_u32 s3, s9, 0
	v_writelane_b32 v254, s2, 5
	s_barrier
	s_nop 0
	v_writelane_b32 v254, s3, 6
	s_add_u32 s2, s8, 0x35cc0700
	s_addc_u32 s3, s9, 0
	s_add_u32 s82, s8, 0x35cc0800
	s_addc_u32 s83, s9, 0
	s_add_u32 s84, s8, 0x35cc0900
	s_addc_u32 s85, s9, 0
	s_add_u32 s86, s8, 0x35cc0a00
	s_addc_u32 s87, s9, 0
	s_add_u32 s88, s8, 0x35cc0b00
	s_addc_u32 s89, s9, 0
	s_add_u32 s90, s8, 0x35cc0c00
	s_addc_u32 s91, s9, 0
	s_add_u32 s92, s8, 0x35cc0d00
	s_addc_u32 s93, s9, 0
	s_add_u32 s94, s8, 0x35cc0e00
	s_addc_u32 s95, s9, 0
	s_add_u32 s96, s8, 0x35cc0f00
	s_addc_u32 s97, s9, 0
	s_add_u32 s4, s8, 0x35cc1000
	s_addc_u32 s5, s9, 0
	s_add_u32 s6, s8, 0x35cc1100
	s_addc_u32 s7, s9, 0
	s_add_u32 s78, s8, 0x35cc1200
	s_addc_u32 s79, s9, 0
	s_add_u32 s80, s8, 0x35cc1300
	s_addc_u32 s81, s9, 0
	v_writelane_b32 v254, s2, 7
	s_cmp_eq_u32 s24, 15
	s_nop 0
	v_writelane_b32 v254, s3, 8
	s_cselect_b64 s[2:3], -1, 0
	v_writelane_b32 v254, s2, 9
	s_cmp_eq_u32 s24, 14
	s_nop 0
	v_writelane_b32 v254, s3, 10
	s_cselect_b64 s[2:3], -1, 0
	v_writelane_b32 v254, s2, 11
	s_cmp_eq_u32 s24, 13
	s_nop 0
	v_writelane_b32 v254, s3, 12
	s_cselect_b64 s[2:3], -1, 0
	v_writelane_b32 v254, s2, 13
	s_cmp_eq_u32 s24, 12
	s_nop 0
	v_writelane_b32 v254, s3, 14
	s_cselect_b64 s[2:3], -1, 0
	v_writelane_b32 v254, s2, 15
	s_cmp_eq_u32 s24, 11
	s_nop 0
	v_writelane_b32 v254, s3, 16
	s_cselect_b64 s[2:3], -1, 0
	v_writelane_b32 v254, s2, 17
	s_cmp_eq_u32 s24, 10
	s_nop 0
	v_writelane_b32 v254, s3, 18
	s_cselect_b64 s[2:3], -1, 0
	v_writelane_b32 v254, s2, 19
	s_cmp_eq_u32 s24, 9
	s_nop 0
	v_writelane_b32 v254, s3, 20
	s_cselect_b64 s[2:3], -1, 0
	v_writelane_b32 v254, s2, 21
	s_cmp_eq_u32 s24, 8
	s_nop 0
	v_writelane_b32 v254, s3, 22
	s_cselect_b64 s[2:3], -1, 0
	v_writelane_b32 v254, s2, 23
	s_cmp_eq_u32 s24, 7
	s_nop 0
	v_writelane_b32 v254, s3, 24
	s_cselect_b64 s[2:3], -1, 0
	v_writelane_b32 v254, s2, 25
	s_cmp_eq_u32 s24, 6
	s_nop 0
	v_writelane_b32 v254, s3, 26
	s_cselect_b64 s[2:3], -1, 0
	v_writelane_b32 v254, s2, 27
	s_cmp_eq_u32 s24, 5
	s_nop 0
	v_writelane_b32 v254, s3, 28
	s_cselect_b64 s[2:3], -1, 0
	v_writelane_b32 v254, s2, 29
	s_cmp_eq_u32 s24, 4
	s_nop 0
	v_writelane_b32 v254, s3, 30
	s_cselect_b64 s[2:3], -1, 0
	v_writelane_b32 v254, s2, 31
	s_cmp_eq_u32 s24, 3
	s_nop 0
	v_writelane_b32 v254, s3, 32
	s_cselect_b64 s[2:3], -1, 0
	v_writelane_b32 v254, s2, 33
	s_cmp_eq_u32 s24, 2
	s_nop 0
	v_writelane_b32 v254, s3, 34
	s_cselect_b64 s[2:3], -1, 0
	v_writelane_b32 v254, s2, 35
	s_cmp_eq_u32 s24, 1
	s_nop 0
	v_writelane_b32 v254, s3, 36
	s_cselect_b64 s[2:3], -1, 0
	v_writelane_b32 v254, s2, 37
	s_cmp_eq_u32 s24, 0
	s_nop 0
	v_writelane_b32 v254, s3, 38
	s_cselect_b64 s[2:3], -1, 0
	v_writelane_b32 v254, s2, 39
	s_nop 1
	v_writelane_b32 v254, s3, 40
	s_lshl_b32 s2, s24, 8
	s_add_u32 s2, s10, s2
	s_addc_u32 s3, s11, 0
	s_add_u32 s10, s2, 0x1400
	s_addc_u32 s11, s3, 0
	v_writelane_b32 v254, s10, 41
	s_add_u32 s2, s2, 0x2400
	s_addc_u32 s3, s3, 0
	v_writelane_b32 v254, s11, 42
	v_writelane_b32 v254, s2, 43
	s_nop 1
	v_writelane_b32 v254, s3, 44
	s_add_u32 s2, s8, 0x35cc3400
	s_addc_u32 s3, s9, 0
	v_writelane_b32 v254, s2, 45
	s_nop 1
	v_writelane_b32 v254, s3, 46
	s_add_u32 s2, s8, 0x35cc3500
	s_addc_u32 s3, s9, 0
	v_writelane_b32 v254, s2, 47
	s_nop 1
	v_writelane_b32 v254, s3, 48
	v_readfirstlane_b32 s98, v222
	s_nop 3
	s_lshr_b32 s98, s98, 6
	s_cmp_eq_u32 s98, 1
	s_cbranch_scc0 .Lxbi0_skip
	buffer_inv sc1
	s_waitcnt vmcnt(0)
.Lxbi0_skip:
	s_mov_b64 s[8:9], exec
	v_readlane_b32 s2, v254, 0
	v_readlane_b32 s3, v254, 1
	s_and_b64 s[2:3], s[8:9], s[2:3]
	s_mov_b64 exec, s[2:3]
	s_cbranch_execz .LBB0_136
	s_add_i32 s2, 0, 0x27ff0
	v_mov_b32_e32 v0, s2
	s_waitcnt vmcnt(0) expcnt(0) lgkmcnt(0)
	ds_read_b32 v2, v0
	s_add_i32 s2, 0, 0x27ff4
	v_mov_b32_e32 v0, s2
	ds_read_b32 v0, v0
	s_waitcnt lgkmcnt(1)
	v_cmp_ne_u32_e32 vcc, 0, v2
	s_cbranch_vccnz .LBB0_100
	s_mov_b32 s10, 1
	v_mov_b32_e32 v16, 0
	s_branch .LBB0_88

; __device__ __forceinline__ unsigned xb_ld(unsigned* p)              { return __hip_atomic_load(p, __ATOMIC_RELAXED, __HIP_MEMORY_SCOPE_AGENT); }
; __device__ __forceinline__ unsigned xb_add(unsigned* p, unsigned v) { return __hip_atomic_fetch_add(p, v, __ATOMIC_RELAXED, __HIP_MEMORY_SCOPE_AGENT); }
; #define XB_SPIN(cond, bar) do { unsigned _sp = 0; while (cond) { __builtin_amdgcn_s_sleep(1); \
;     if ((++_sp & 255u) == 0u) { if (xb_ld(&(bar)[XB_TMO])) break; if (_sp > XB_SPIN_CAP) { atomicAdd(&(bar)[XB_TMO], 1u); break; } } } } while (0)
; __device__ __forceinline__ void xcd_barrier(const XcdBarrier& b) {
;     ...
;         const unsigned old = xb_add(&bar[XB_XSUB(b.x)], 1u);
;         const unsigned gen = old / nloc;
;         if (old + 1u == (gen + 1u) * nloc) {
;             __builtin_amdgcn_fence(__ATOMIC_RELEASE, "agent");
;             asm volatile("s_waitcnt vmcnt(0)" ::: "memory");
;             const unsigned og = xb_add(&bar[XB_TOP], 1u);
;             const unsigned tg = og / nx;
;             if (og + 1u == (tg + 1u) * nx) xb_add(&bar[XB_TOPGEN], 1u);
;             else XB_SPIN(xb_ld(&bar[XB_TOPGEN]) == tg, bar);
;             __builtin_amdgcn_fence(__ATOMIC_ACQUIRE, "agent");
;             xb_add(&bar[XB_XGEN(b.x)], 1u);
;             asm volatile("s_waitcnt vmcnt(0)" ::: "memory");
;         } else {
;             XB_SPIN(xb_ld(&bar[XB_XGEN(b.x)]) == gen, bar);
;             __builtin_amdgcn_fence(__ATOMIC_ACQUIRE, "agent");
;             asm volatile("s_waitcnt vmcnt(0)" ::: "memory");
.LBB0_100:
	s_mov_b32 s2, 0x27ff0
	s_mov_b32 s3, 0x27ff4
	v_readlane_b32 s12, v254, 41
	v_readlane_b32 s13, v254, 42
	s_waitcnt lgkmcnt(0)
	v_mov_b32_e32 v0, s2
	v_mov_b32_e32 v4, s3
	ds_read_b32 v3, v0
	ds_read_b32 v2, v4
	v_mov_b32_e32 v5, 0
	v_mov_b32_e32 v6, 1
	s_nop 1
	global_atomic_add v6, v5, v6, s[12:13] sc0
	v_readlane_b32 s2, v254, 45
	v_readlane_b32 s3, v254, 46
	s_waitcnt vmcnt(0) lgkmcnt(0)
	v_cvt_f32_u32_e32 v0, v3
	v_sub_u32_e32 v4, 0, v3
	v_rcp_iflag_f32_e32 v0, v0
	s_nop 0
	v_mul_f32_e32 v0, 0x4f7ffffe, v0
	v_cvt_u32_f32_e32 v0, v0
	v_mul_lo_u32 v4, v4, v0
	v_mul_hi_u32 v4, v0, v4
	v_add_u32_e32 v0, v0, v4
	v_mul_hi_u32 v0, v6, v0
	v_mul_lo_u32 v4, v0, v3
	v_sub_u32_e32 v4, v6, v4
	v_add_u32_e32 v7, 1, v0
	v_cmp_ge_u32_e32 vcc, v4, v3
	s_nop 1
	v_cndmask_b32_e32 v0, v0, v7, vcc
	v_sub_u32_e32 v7, v4, v3
	v_cndmask_b32_e32 v4, v4, v7, vcc
	v_add_u32_e32 v7, 1, v0
	v_cmp_ge_u32_e32 vcc, v4, v3
	s_nop 1
	v_cndmask_b32_e32 v0, v0, v7, vcc
	v_add_u32_e32 v7, 1, v0
	v_mul_lo_u32 v4, v7, v3
	v_mul_lo_u32 v7, v7, v2
	v_add_u32_e32 v6, 1, v6
	v_cmp_ne_u32_e32 vcc, v6, v4
	s_mov_b32 s98, 0
	s_cbranch_vccnz .Lxb0_early
	s_nop 0
	buffer_wbl2 sc1
	s_waitcnt vmcnt(0)
	v_mov_b32_e32 v6, 1
	global_atomic_add v5, v6, s[2:3]
	s_branch .Lxb0_early
.Lxb0_early:
	s_nop 0
.Lxb0_poll:
	global_load_dword v6, v5, s[2:3] sc1
	s_waitcnt vmcnt(0)
	v_cmp_lt_u32_e32 vcc, v6, v7
	s_cbranch_vccz .Lxb0_done
	s_sleep 1
	s_add_i32 s98, s98, 1
	s_cmp_lt_u32 s98, 0x40000
	s_cbranch_scc1 .Lxb0_poll

; __device__ __forceinline__ void xcd_barrier(const XcdBarrier& b) {
;     asm volatile("s_waitcnt vmcnt(0)" ::: "memory");
;     __syncthreads();
;     if (threadIdx.x == 0) {
;         unsigned* bar = b.bar;
;         __builtin_amdgcn_s_waitcnt(0);
;         unsigned nloc = b.st[0], nx = b.st[1];
;         if (nloc == 0u) { xcd_barrier_complete(bar, b.x, nloc, nx); b.st[0] = nloc; b.st[1] = nx; }
.LBB0_453:
	s_waitcnt vmcnt(0)
	s_waitcnt vmcnt(0) lgkmcnt(0)
	s_barrier
	v_readfirstlane_b32 s98, v222
	s_nop 3
	s_lshr_b32 s98, s98, 6
	s_cmp_eq_u32 s98, 1
	s_cbranch_scc0 .Lxbi1_skip
	buffer_inv sc1
	s_waitcnt vmcnt(0)
.Lxbi1_skip:
	s_mov_b64 s[8:9], exec
	v_readlane_b32 s2, v254, 0
	v_readlane_b32 s3, v254, 1
	s_and_b64 s[2:3], s[8:9], s[2:3]
	s_mov_b64 exec, s[2:3]
	s_cbranch_execz .LBB0_505
	v_readlane_b32 s2, v254, 59
	s_waitcnt vmcnt(0) expcnt(0) lgkmcnt(0)
	s_nop 0
	v_mov_b32_e32 v0, s2
	ds_read_b32 v3, v0
	v_readlane_b32 s2, v254, 60
	s_waitcnt lgkmcnt(0)
	v_cmp_ne_u32_e32 vcc, 0, v3
	v_mov_b32_e32 v0, s2
	ds_read_b32 v2, v0
	s_cbranch_vccnz .LBB0_469
	s_mov_b32 s14, 1
	s_branch .LBB0_457

; __device__ __forceinline__ unsigned xb_ld(unsigned* p)              { return __hip_atomic_load(p, __ATOMIC_RELAXED, __HIP_MEMORY_SCOPE_AGENT); }
; __device__ __forceinline__ unsigned xb_add(unsigned* p, unsigned v) { return __hip_atomic_fetch_add(p, v, __ATOMIC_RELAXED, __HIP_MEMORY_SCOPE_AGENT); }
; #define XB_SPIN(cond, bar) do { unsigned _sp = 0; while (cond) { __builtin_amdgcn_s_sleep(1); \
;     if ((++_sp & 255u) == 0u) { if (xb_ld(&(bar)[XB_TMO])) break; if (_sp > XB_SPIN_CAP) { atomicAdd(&(bar)[XB_TMO], 1u); break; } } } } while (0)
; __device__ __forceinline__ void xcd_barrier(const XcdBarrier& b) {
;     ...
;         const unsigned old = xb_add(&bar[XB_XSUB(b.x)], 1u);
;         const unsigned gen = old / nloc;
;         if (old + 1u == (gen + 1u) * nloc) {
;             __builtin_amdgcn_fence(__ATOMIC_RELEASE, "agent");
;             asm volatile("s_waitcnt vmcnt(0)" ::: "memory");
;             const unsigned og = xb_add(&bar[XB_TOP], 1u);
;             const unsigned tg = og / nx;
;             if (og + 1u == (tg + 1u) * nx) xb_add(&bar[XB_TOPGEN], 1u);
;             else XB_SPIN(xb_ld(&bar[XB_TOPGEN]) == tg, bar);
;             __builtin_amdgcn_fence(__ATOMIC_ACQUIRE, "agent");
;             xb_add(&bar[XB_XGEN(b.x)], 1u);
;             asm volatile("s_waitcnt vmcnt(0)" ::: "memory");
;         } else {
;             XB_SPIN(xb_ld(&bar[XB_XGEN(b.x)]) == gen, bar);
;             __builtin_amdgcn_fence(__ATOMIC_ACQUIRE, "agent");
;             asm volatile("s_waitcnt vmcnt(0)" ::: "memory");
.LBB0_469:
	v_readlane_b32 s2, v254, 59
	v_readlane_b32 s3, v254, 60
	v_readlane_b32 s12, v254, 41
	v_readlane_b32 s13, v254, 42
	s_waitcnt lgkmcnt(0)
	v_mov_b32_e32 v0, s2
	v_mov_b32_e32 v4, s3
	ds_read_b32 v3, v0
	ds_read_b32 v2, v4
	v_mov_b32_e32 v5, 0
	v_mov_b32_e32 v6, 1
	s_nop 1
	global_atomic_add v6, v5, v6, s[12:13] sc0
	v_readlane_b32 s2, v254, 45
	v_readlane_b32 s3, v254, 46
	s_waitcnt vmcnt(0) lgkmcnt(0)
	v_cvt_f32_u32_e32 v0, v3
	v_sub_u32_e32 v4, 0, v3
	v_rcp_iflag_f32_e32 v0, v0
	s_nop 0
	v_mul_f32_e32 v0, 0x4f7ffffe, v0
	v_cvt_u32_f32_e32 v0, v0
	v_mul_lo_u32 v4, v4, v0
	v_mul_hi_u32 v4, v0, v4
	v_add_u32_e32 v0, v0, v4
	v_mul_hi_u32 v0, v6, v0
	v_mul_lo_u32 v4, v0, v3
	v_sub_u32_e32 v4, v6, v4
	v_add_u32_e32 v7, 1, v0
	v_cmp_ge_u32_e32 vcc, v4, v3
	s_nop 1
	v_cndmask_b32_e32 v0, v0, v7, vcc
	v_sub_u32_e32 v7, v4, v3
	v_cndmask_b32_e32 v4, v4, v7, vcc
	v_add_u32_e32 v7, 1, v0
	v_cmp_ge_u32_e32 vcc, v4, v3
	s_nop 1
	v_cndmask_b32_e32 v0, v0, v7, vcc
	v_add_u32_e32 v7, 1, v0
	v_mul_lo_u32 v4, v7, v3
	v_mul_lo_u32 v7, v7, v2
	v_add_u32_e32 v6, 1, v6
	v_cmp_ne_u32_e32 vcc, v6, v4
	s_mov_b32 s98, 0
	s_cbranch_vccnz .Lxb1_early
	s_nop 0
	buffer_wbl2 sc1
	s_waitcnt vmcnt(0)
	v_mov_b32_e32 v6, 1
	global_atomic_add v5, v6, s[2:3]
	s_branch .Lxb1_early
.Lxb1_early:
	s_nop 0
.Lxb1_poll:
	global_load_dword v6, v5, s[2:3] sc1
	s_waitcnt vmcnt(0)
	v_cmp_lt_u32_e32 vcc, v6, v7
	s_cbranch_vccz .Lxb1_done
	s_sleep 1
	s_add_i32 s98, s98, 1
	s_cmp_lt_u32 s98, 0x40000
	s_cbranch_scc1 .Lxb1_poll

; __device__ __forceinline__ void xcd_barrier(const XcdBarrier& b) {
;     asm volatile("s_waitcnt vmcnt(0)" ::: "memory");
;     __syncthreads();
;     if (threadIdx.x == 0) {
.LBB0_625:
	s_waitcnt vmcnt(0)
	s_waitcnt lgkmcnt(0)
	s_barrier
	v_readfirstlane_b32 s98, v222
	s_nop 3
	s_lshr_b32 s98, s98, 6
	s_cmp_eq_u32 s98, 1
	s_cbranch_scc0 .Lxbi2_skip
	buffer_inv sc1
	s_waitcnt vmcnt(0)

; __device__ __forceinline__ unsigned xb_ld(unsigned* p)              { return __hip_atomic_load(p, __ATOMIC_RELAXED, __HIP_MEMORY_SCOPE_AGENT); }
; __device__ __forceinline__ unsigned xb_add(unsigned* p, unsigned v) { return __hip_atomic_fetch_add(p, v, __ATOMIC_RELAXED, __HIP_MEMORY_SCOPE_AGENT); }
; #define XB_SPIN(cond, bar) do { unsigned _sp = 0; while (cond) { __builtin_amdgcn_s_sleep(1); \
;     if ((++_sp & 255u) == 0u) { if (xb_ld(&(bar)[XB_TMO])) break; if (_sp > XB_SPIN_CAP) { atomicAdd(&(bar)[XB_TMO], 1u); break; } } } } while (0)
; __device__ __forceinline__ void xcd_barrier(const XcdBarrier& b) {
;     ...
;         const unsigned old = xb_add(&bar[XB_XSUB(b.x)], 1u);
;         const unsigned gen = old / nloc;
;         if (old + 1u == (gen + 1u) * nloc) {
;             __builtin_amdgcn_fence(__ATOMIC_RELEASE, "agent");
;             asm volatile("s_waitcnt vmcnt(0)" ::: "memory");
;             const unsigned og = xb_add(&bar[XB_TOP], 1u);
;             const unsigned tg = og / nx;
;             if (og + 1u == (tg + 1u) * nx) xb_add(&bar[XB_TOPGEN], 1u);
;             else XB_SPIN(xb_ld(&bar[XB_TOPGEN]) == tg, bar);
;             __builtin_amdgcn_fence(__ATOMIC_ACQUIRE, "agent");
;             xb_add(&bar[XB_XGEN(b.x)], 1u);
;             asm volatile("s_waitcnt vmcnt(0)" ::: "memory");
;         } else {
;             XB_SPIN(xb_ld(&bar[XB_XGEN(b.x)]) == gen, bar);
;             __builtin_amdgcn_fence(__ATOMIC_ACQUIRE, "agent");
;             asm volatile("s_waitcnt vmcnt(0)" ::: "memory");
.LBB0_641:
	v_readlane_b32 s2, v254, 59
	v_readlane_b32 s3, v254, 60
	v_readlane_b32 s12, v254, 41
	v_readlane_b32 s13, v254, 42
	s_waitcnt lgkmcnt(0)
	v_mov_b32_e32 v0, s2
	v_mov_b32_e32 v4, s3
	ds_read_b32 v3, v0
	ds_read_b32 v2, v4
	v_mov_b32_e32 v5, 0
	v_mov_b32_e32 v6, 1
	s_nop 1
	global_atomic_add v6, v5, v6, s[12:13] sc0
	v_readlane_b32 s2, v254, 45
	v_readlane_b32 s3, v254, 46
	s_waitcnt vmcnt(0) lgkmcnt(0)
	v_cvt_f32_u32_e32 v0, v3
	v_sub_u32_e32 v4, 0, v3
	v_rcp_iflag_f32_e32 v0, v0
	s_nop 0
	v_mul_f32_e32 v0, 0x4f7ffffe, v0
	v_cvt_u32_f32_e32 v0, v0
	v_mul_lo_u32 v4, v4, v0
	v_mul_hi_u32 v4, v0, v4
	v_add_u32_e32 v0, v0, v4
	v_mul_hi_u32 v0, v6, v0
	v_mul_lo_u32 v4, v0, v3
	v_sub_u32_e32 v4, v6, v4
	v_add_u32_e32 v7, 1, v0
	v_cmp_ge_u32_e32 vcc, v4, v3
	s_nop 1
	v_cndmask_b32_e32 v0, v0, v7, vcc
	v_sub_u32_e32 v7, v4, v3
	v_cndmask_b32_e32 v4, v4, v7, vcc
	v_add_u32_e32 v7, 1, v0
	v_cmp_ge_u32_e32 vcc, v4, v3
	s_nop 1
	v_cndmask_b32_e32 v0, v0, v7, vcc
	v_add_u32_e32 v7, 1, v0
	v_mul_lo_u32 v4, v7, v3
	v_mul_lo_u32 v7, v7, v2
	v_add_u32_e32 v6, 1, v6
	v_cmp_ne_u32_e32 vcc, v6, v4
	s_mov_b32 s98, 0
	s_cbranch_vccnz .Lxb2_early
	s_nop 0
	buffer_wbl2 sc1
	s_waitcnt vmcnt(0)
	v_mov_b32_e32 v6, 1
	global_atomic_add v5, v6, s[2:3]
	s_branch .Lxb2_early
.Lxb2_early:
	s_nop 0
.Lxb2_poll:
	global_load_dword v6, v5, s[2:3] sc1
	s_waitcnt vmcnt(0)
	v_cmp_lt_u32_e32 vcc, v6, v7
	s_cbranch_vccz .Lxb2_done
	s_sleep 1
	s_add_i32 s98, s98, 1
	s_cmp_lt_u32 s98, 0x40000
	s_cbranch_scc1 .Lxb2_poll

; __device__ __forceinline__ void xcd_barrier(const XcdBarrier& b) {
;     asm volatile("s_waitcnt vmcnt(0)" ::: "memory");
;     __syncthreads();
;     if (threadIdx.x == 0) {
.LBB0_725:
	s_or_b64 exec, exec, s[8:9]
	s_waitcnt vmcnt(0)
	s_barrier
	v_readfirstlane_b32 s98, v222
	s_nop 3
	s_lshr_b32 s98, s98, 6
	s_cmp_eq_u32 s98, 1
	s_cbranch_scc0 .Lxbi3_skip
	buffer_inv sc1
	s_waitcnt vmcnt(0)

; __device__ __forceinline__ unsigned xb_ld(unsigned* p)              { return __hip_atomic_load(p, __ATOMIC_RELAXED, __HIP_MEMORY_SCOPE_AGENT); }
; __device__ __forceinline__ unsigned xb_add(unsigned* p, unsigned v) { return __hip_atomic_fetch_add(p, v, __ATOMIC_RELAXED, __HIP_MEMORY_SCOPE_AGENT); }
; #define XB_SPIN(cond, bar) do { unsigned _sp = 0; while (cond) { __builtin_amdgcn_s_sleep(1); \
;     if ((++_sp & 255u) == 0u) { if (xb_ld(&(bar)[XB_TMO])) break; if (_sp > XB_SPIN_CAP) { atomicAdd(&(bar)[XB_TMO], 1u); break; } } } } while (0)
; __device__ __forceinline__ void xcd_barrier(const XcdBarrier& b) {
;     ...
;         const unsigned old = xb_add(&bar[XB_XSUB(b.x)], 1u);
;         const unsigned gen = old / nloc;
;         if (old + 1u == (gen + 1u) * nloc) {
;             __builtin_amdgcn_fence(__ATOMIC_RELEASE, "agent");
;             asm volatile("s_waitcnt vmcnt(0)" ::: "memory");
;             const unsigned og = xb_add(&bar[XB_TOP], 1u);
;             const unsigned tg = og / nx;
;             if (og + 1u == (tg + 1u) * nx) xb_add(&bar[XB_TOPGEN], 1u);
;             else XB_SPIN(xb_ld(&bar[XB_TOPGEN]) == tg, bar);
;             __builtin_amdgcn_fence(__ATOMIC_ACQUIRE, "agent");
;             xb_add(&bar[XB_XGEN(b.x)], 1u);
;             asm volatile("s_waitcnt vmcnt(0)" ::: "memory");
;         } else {
;             XB_SPIN(xb_ld(&bar[XB_XGEN(b.x)]) == gen, bar);
;             __builtin_amdgcn_fence(__ATOMIC_ACQUIRE, "agent");
;             asm volatile("s_waitcnt vmcnt(0)" ::: "memory");
.LBB0_741:
	v_readlane_b32 s2, v254, 59
	v_readlane_b32 s3, v254, 60
	v_readlane_b32 s12, v254, 41
	v_readlane_b32 s13, v254, 42
	s_waitcnt lgkmcnt(0)
	v_mov_b32_e32 v0, s2
	v_mov_b32_e32 v4, s3
	ds_read_b32 v3, v0
	ds_read_b32 v2, v4
	v_mov_b32_e32 v5, 0
	v_mov_b32_e32 v6, 1
	s_nop 1
	global_atomic_add v6, v5, v6, s[12:13] sc0
	v_readlane_b32 s2, v254, 45
	v_readlane_b32 s3, v254, 46
	s_waitcnt vmcnt(0) lgkmcnt(0)
	v_cvt_f32_u32_e32 v0, v3
	v_sub_u32_e32 v4, 0, v3
	v_rcp_iflag_f32_e32 v0, v0
	s_nop 0
	v_mul_f32_e32 v0, 0x4f7ffffe, v0
	v_cvt_u32_f32_e32 v0, v0
	v_mul_lo_u32 v4, v4, v0
	v_mul_hi_u32 v4, v0, v4
	v_add_u32_e32 v0, v0, v4
	v_mul_hi_u32 v0, v6, v0
	v_mul_lo_u32 v4, v0, v3
	v_sub_u32_e32 v4, v6, v4
	v_add_u32_e32 v7, 1, v0
	v_cmp_ge_u32_e32 vcc, v4, v3
	s_nop 1
	v_cndmask_b32_e32 v0, v0, v7, vcc
	v_sub_u32_e32 v7, v4, v3
	v_cndmask_b32_e32 v4, v4, v7, vcc
	v_add_u32_e32 v7, 1, v0
	v_cmp_ge_u32_e32 vcc, v4, v3
	s_nop 1
	v_cndmask_b32_e32 v0, v0, v7, vcc
	v_add_u32_e32 v7, 1, v0
	v_mul_lo_u32 v4, v7, v3
	v_mul_lo_u32 v7, v7, v2
	v_add_u32_e32 v6, 1, v6
	v_cmp_ne_u32_e32 vcc, v6, v4
	s_mov_b32 s98, 0
	s_cbranch_vccnz .Lxb3_early
	s_nop 0
	buffer_wbl2 sc1
	s_waitcnt vmcnt(0)
	v_mov_b32_e32 v6, 1
	global_atomic_add v5, v6, s[2:3]
	s_branch .Lxb3_early
.Lxb3_early:
	s_nop 0
.Lxb3_poll:
	global_load_dword v6, v5, s[2:3] sc1
	s_waitcnt vmcnt(0)
	v_cmp_lt_u32_e32 vcc, v6, v7
	s_cbranch_vccz .Lxb3_done
	s_sleep 1
	s_add_i32 s98, s98, 1
	s_cmp_lt_u32 s98, 0x40000
	s_cbranch_scc1 .Lxb3_poll

; __device__ __forceinline__ void xcd_barrier(const XcdBarrier& b) {
;     asm volatile("s_waitcnt vmcnt(0)" ::: "memory");
;     __syncthreads();
;     if (threadIdx.x == 0) {
.Ltc_skipcall_2:
.LBB0_917:
	s_waitcnt vmcnt(0)
	s_waitcnt lgkmcnt(0)
	s_barrier
	v_readfirstlane_b32 s98, v222
	s_nop 3
	s_lshr_b32 s98, s98, 6
	s_cmp_eq_u32 s98, 1
	s_cbranch_scc0 .Lxbi4_skip
	buffer_inv sc1
	s_waitcnt vmcnt(0)

; __device__ __forceinline__ unsigned xb_ld(unsigned* p)              { return __hip_atomic_load(p, __ATOMIC_RELAXED, __HIP_MEMORY_SCOPE_AGENT); }
; __device__ __forceinline__ unsigned xb_add(unsigned* p, unsigned v) { return __hip_atomic_fetch_add(p, v, __ATOMIC_RELAXED, __HIP_MEMORY_SCOPE_AGENT); }
; #define XB_SPIN(cond, bar) do { unsigned _sp = 0; while (cond) { __builtin_amdgcn_s_sleep(1); \
;     if ((++_sp & 255u) == 0u) { if (xb_ld(&(bar)[XB_TMO])) break; if (_sp > XB_SPIN_CAP) { atomicAdd(&(bar)[XB_TMO], 1u); break; } } } } while (0)
; __device__ __forceinline__ void xcd_barrier(const XcdBarrier& b) {
;     ...
;         const unsigned old = xb_add(&bar[XB_XSUB(b.x)], 1u);
;         const unsigned gen = old / nloc;
;         if (old + 1u == (gen + 1u) * nloc) {
;             __builtin_amdgcn_fence(__ATOMIC_RELEASE, "agent");
;             asm volatile("s_waitcnt vmcnt(0)" ::: "memory");
;             const unsigned og = xb_add(&bar[XB_TOP], 1u);
;             const unsigned tg = og / nx;
;             if (og + 1u == (tg + 1u) * nx) xb_add(&bar[XB_TOPGEN], 1u);
;             else XB_SPIN(xb_ld(&bar[XB_TOPGEN]) == tg, bar);
;             __builtin_amdgcn_fence(__ATOMIC_ACQUIRE, "agent");
;             xb_add(&bar[XB_XGEN(b.x)], 1u);
;             asm volatile("s_waitcnt vmcnt(0)" ::: "memory");
;         } else {
;             XB_SPIN(xb_ld(&bar[XB_XGEN(b.x)]) == gen, bar);
;             __builtin_amdgcn_fence(__ATOMIC_ACQUIRE, "agent");
;             asm volatile("s_waitcnt vmcnt(0)" ::: "memory");
.LBB0_933:
	v_readlane_b32 s2, v254, 59
	v_readlane_b32 s3, v254, 60
	v_readlane_b32 s12, v254, 41
	v_readlane_b32 s13, v254, 42
	s_waitcnt lgkmcnt(0)
	v_mov_b32_e32 v0, s2
	v_mov_b32_e32 v4, s3
	ds_read_b32 v3, v0
	ds_read_b32 v2, v4
	v_mov_b32_e32 v5, 0
	v_mov_b32_e32 v6, 1
	s_nop 1
	global_atomic_add v6, v5, v6, s[12:13] sc0
	v_readlane_b32 s2, v254, 45
	v_readlane_b32 s3, v254, 46
	s_waitcnt vmcnt(0) lgkmcnt(0)
	v_cvt_f32_u32_e32 v0, v3
	v_sub_u32_e32 v4, 0, v3
	v_rcp_iflag_f32_e32 v0, v0
	s_nop 0
	v_mul_f32_e32 v0, 0x4f7ffffe, v0
	v_cvt_u32_f32_e32 v0, v0
	v_mul_lo_u32 v4, v4, v0
	v_mul_hi_u32 v4, v0, v4
	v_add_u32_e32 v0, v0, v4
	v_mul_hi_u32 v0, v6, v0
	v_mul_lo_u32 v4, v0, v3
	v_sub_u32_e32 v4, v6, v4
	v_add_u32_e32 v7, 1, v0
	v_cmp_ge_u32_e32 vcc, v4, v3
	s_nop 1
	v_cndmask_b32_e32 v0, v0, v7, vcc
	v_sub_u32_e32 v7, v4, v3
	v_cndmask_b32_e32 v4, v4, v7, vcc
	v_add_u32_e32 v7, 1, v0
	v_cmp_ge_u32_e32 vcc, v4, v3
	s_nop 1
	v_cndmask_b32_e32 v0, v0, v7, vcc
	v_add_u32_e32 v7, 1, v0
	v_mul_lo_u32 v4, v7, v3
	v_mul_lo_u32 v7, v7, v2
	v_add_u32_e32 v6, 1, v6
	v_cmp_ne_u32_e32 vcc, v6, v4
	s_mov_b32 s98, 0
	s_cbranch_vccnz .Lxb4_early
	s_nop 0
	buffer_wbl2 sc1
	s_waitcnt vmcnt(0)
	v_mov_b32_e32 v6, 1
	global_atomic_add v5, v6, s[2:3]
	s_branch .Lxb4_early
.Lxb4_early:
	s_nop 0
.Lxb4_poll:
	global_load_dword v6, v5, s[2:3] sc1
	s_waitcnt vmcnt(0)
	v_cmp_lt_u32_e32 vcc, v6, v7
	s_cbranch_vccz .Lxb4_done
	s_sleep 1
	s_add_i32 s98, s98, 1
	s_cmp_lt_u32 s98, 0x40000
	s_cbranch_scc1 .Lxb4_poll

; __device__ __forceinline__ unsigned xb_ld(unsigned* p)              { return __hip_atomic_load(p, __ATOMIC_RELAXED, __HIP_MEMORY_SCOPE_AGENT); }
; __device__ __forceinline__ unsigned xb_add(unsigned* p, unsigned v) { return __hip_atomic_fetch_add(p, v, __ATOMIC_RELAXED, __HIP_MEMORY_SCOPE_AGENT); }
; #define XB_SPIN(cond, bar) do { unsigned _sp = 0; while (cond) { __builtin_amdgcn_s_sleep(1); \
;     if ((++_sp & 255u) == 0u) { if (xb_ld(&(bar)[XB_TMO])) break; if (_sp > XB_SPIN_CAP) { atomicAdd(&(bar)[XB_TMO], 1u); break; } } } } while (0)
; __device__ __forceinline__ void xcd_barrier(const XcdBarrier& b) {
;     ...
;         const unsigned old = xb_add(&bar[XB_XSUB(b.x)], 1u);
;         const unsigned gen = old / nloc;
;         if (old + 1u == (gen + 1u) * nloc) {
;             __builtin_amdgcn_fence(__ATOMIC_RELEASE, "agent");
;             asm volatile("s_waitcnt vmcnt(0)" ::: "memory");
;             const unsigned og = xb_add(&bar[XB_TOP], 1u);
;             const unsigned tg = og / nx;
;             if (og + 1u == (tg + 1u) * nx) xb_add(&bar[XB_TOPGEN], 1u);
;             else XB_SPIN(xb_ld(&bar[XB_TOPGEN]) == tg, bar);
;             __builtin_amdgcn_fence(__ATOMIC_ACQUIRE, "agent");
;             xb_add(&bar[XB_XGEN(b.x)], 1u);
;             asm volatile("s_waitcnt vmcnt(0)" ::: "memory");
;         } else {
;             XB_SPIN(xb_ld(&bar[XB_XGEN(b.x)]) == gen, bar);
;             __builtin_amdgcn_fence(__ATOMIC_ACQUIRE, "agent");
;             asm volatile("s_waitcnt vmcnt(0)" ::: "memory");
.LBB0_1076:
	v_readlane_b32 s2, v254, 59
	v_readlane_b32 s3, v254, 60
	v_readlane_b32 s12, v254, 41
	v_readlane_b32 s13, v254, 42
	s_waitcnt lgkmcnt(0)
	v_mov_b32_e32 v0, s2
	v_mov_b32_e32 v4, s3
	ds_read_b32 v3, v0
	ds_read_b32 v2, v4
	v_mov_b32_e32 v5, 0
	v_mov_b32_e32 v6, 1
	s_nop 1
	global_atomic_add v6, v5, v6, s[12:13] sc0
	v_readlane_b32 s2, v254, 45
	v_readlane_b32 s3, v254, 46
	s_waitcnt vmcnt(0) lgkmcnt(0)
	v_cvt_f32_u32_e32 v0, v3
	v_sub_u32_e32 v4, 0, v3
	v_rcp_iflag_f32_e32 v0, v0
	s_nop 0
	v_mul_f32_e32 v0, 0x4f7ffffe, v0
	v_cvt_u32_f32_e32 v0, v0
	v_mul_lo_u32 v4, v4, v0
	v_mul_hi_u32 v4, v0, v4
	v_add_u32_e32 v0, v0, v4
	v_mul_hi_u32 v0, v6, v0
	v_mul_lo_u32 v4, v0, v3
	v_sub_u32_e32 v4, v6, v4
	v_add_u32_e32 v7, 1, v0
	v_cmp_ge_u32_e32 vcc, v4, v3
	s_nop 1
	v_cndmask_b32_e32 v0, v0, v7, vcc
	v_sub_u32_e32 v7, v4, v3
	v_cndmask_b32_e32 v4, v4, v7, vcc
	v_add_u32_e32 v7, 1, v0
	v_cmp_ge_u32_e32 vcc, v4, v3
	s_nop 1
	v_cndmask_b32_e32 v0, v0, v7, vcc
	v_add_u32_e32 v7, 1, v0
	v_mul_lo_u32 v4, v7, v3
	v_mul_lo_u32 v7, v7, v2
	v_add_u32_e32 v6, 1, v6
	v_cmp_ne_u32_e32 vcc, v6, v4
	s_mov_b32 s98, 0
	s_cbranch_vccnz .Lxb5_early
	s_nop 0
	buffer_wbl2 sc1
	s_waitcnt vmcnt(0)
	v_mov_b32_e32 v6, 1
	global_atomic_add v5, v6, s[2:3]
	s_branch .Lxb5_early
.Lxb5_early:
	s_nop 0
.Lxb5_poll:
	global_load_dword v6, v5, s[2:3] sc1
	s_waitcnt vmcnt(0)
	v_cmp_lt_u32_e32 vcc, v6, v7
	s_cbranch_vccz .Lxb5_done
	s_sleep 1
	s_add_i32 s98, s98, 1
	s_cmp_lt_u32 s98, 0x40000
	s_cbranch_scc1 .Lxb5_poll

; __device__ __forceinline__ void xcd_barrier(const XcdBarrier& b) {
;     asm volatile("s_waitcnt vmcnt(0)" ::: "memory");
;     __syncthreads();
;     if (threadIdx.x == 0) {
.LBB0_1126:
	s_waitcnt vmcnt(0)
	s_waitcnt vmcnt(0)
	s_barrier
	v_readfirstlane_b32 s98, v222
	s_nop 3
	s_lshr_b32 s98, s98, 6
	s_cmp_eq_u32 s98, 1
	s_cbranch_scc0 .Lxbi6_skip
	buffer_inv sc1
	s_waitcnt vmcnt(0)

; __device__ __forceinline__ unsigned xb_ld(unsigned* p)              { return __hip_atomic_load(p, __ATOMIC_RELAXED, __HIP_MEMORY_SCOPE_AGENT); }
; __device__ __forceinline__ unsigned xb_add(unsigned* p, unsigned v) { return __hip_atomic_fetch_add(p, v, __ATOMIC_RELAXED, __HIP_MEMORY_SCOPE_AGENT); }
; #define XB_SPIN(cond, bar) do { unsigned _sp = 0; while (cond) { __builtin_amdgcn_s_sleep(1); \
;     if ((++_sp & 255u) == 0u) { if (xb_ld(&(bar)[XB_TMO])) break; if (_sp > XB_SPIN_CAP) { atomicAdd(&(bar)[XB_TMO], 1u); break; } } } } while (0)
; __device__ __forceinline__ void xcd_barrier(const XcdBarrier& b) {
;     ...
;         const unsigned old = xb_add(&bar[XB_XSUB(b.x)], 1u);
;         const unsigned gen = old / nloc;
;         if (old + 1u == (gen + 1u) * nloc) {
;             __builtin_amdgcn_fence(__ATOMIC_RELEASE, "agent");
;             asm volatile("s_waitcnt vmcnt(0)" ::: "memory");
;             const unsigned og = xb_add(&bar[XB_TOP], 1u);
;             const unsigned tg = og / nx;
;             if (og + 1u == (tg + 1u) * nx) xb_add(&bar[XB_TOPGEN], 1u);
;             else XB_SPIN(xb_ld(&bar[XB_TOPGEN]) == tg, bar);
;             __builtin_amdgcn_fence(__ATOMIC_ACQUIRE, "agent");
;             xb_add(&bar[XB_XGEN(b.x)], 1u);
;             asm volatile("s_waitcnt vmcnt(0)" ::: "memory");
;         } else {
;             XB_SPIN(xb_ld(&bar[XB_XGEN(b.x)]) == gen, bar);
;             __builtin_amdgcn_fence(__ATOMIC_ACQUIRE, "agent");
;             asm volatile("s_waitcnt vmcnt(0)" ::: "memory");
.LBB0_1142:
	v_readlane_b32 s2, v254, 59
	v_readlane_b32 s3, v254, 60
	v_readlane_b32 s12, v254, 41
	v_readlane_b32 s13, v254, 42
	s_waitcnt lgkmcnt(0)
	v_mov_b32_e32 v0, s2
	v_mov_b32_e32 v4, s3
	ds_read_b32 v3, v0
	ds_read_b32 v2, v4
	v_mov_b32_e32 v5, 0
	v_mov_b32_e32 v6, 1
	s_nop 1
	global_atomic_add v6, v5, v6, s[12:13] sc0
	v_readlane_b32 s2, v254, 45
	v_readlane_b32 s3, v254, 46
	s_waitcnt vmcnt(0) lgkmcnt(0)
	v_cvt_f32_u32_e32 v0, v3
	v_sub_u32_e32 v4, 0, v3
	v_rcp_iflag_f32_e32 v0, v0
	s_nop 0
	v_mul_f32_e32 v0, 0x4f7ffffe, v0
	v_cvt_u32_f32_e32 v0, v0
	v_mul_lo_u32 v4, v4, v0
	v_mul_hi_u32 v4, v0, v4
	v_add_u32_e32 v0, v0, v4
	v_mul_hi_u32 v0, v6, v0
	v_mul_lo_u32 v4, v0, v3
	v_sub_u32_e32 v4, v6, v4
	v_add_u32_e32 v7, 1, v0
	v_cmp_ge_u32_e32 vcc, v4, v3
	s_nop 1
	v_cndmask_b32_e32 v0, v0, v7, vcc
	v_sub_u32_e32 v7, v4, v3
	v_cndmask_b32_e32 v4, v4, v7, vcc
	v_add_u32_e32 v7, 1, v0
	v_cmp_ge_u32_e32 vcc, v4, v3
	s_nop 1
	v_cndmask_b32_e32 v0, v0, v7, vcc
	v_add_u32_e32 v7, 1, v0
	v_mul_lo_u32 v4, v7, v3
	v_mul_lo_u32 v7, v7, v2
	v_add_u32_e32 v6, 1, v6
	v_cmp_ne_u32_e32 vcc, v6, v4
	s_mov_b32 s98, 0
	s_cbranch_vccnz .Lxb6_early
	s_nop 0
	buffer_wbl2 sc1
	s_waitcnt vmcnt(0)
	v_mov_b32_e32 v6, 1
	global_atomic_add v5, v6, s[2:3]
	s_branch .Lxb6_early
.Lxb6_early:
	s_nop 0
.Lxb6_poll:
	global_load_dword v6, v5, s[2:3] sc1
	s_waitcnt vmcnt(0)
	v_cmp_lt_u32_e32 vcc, v6, v7
	s_cbranch_vccz .Lxb6_done
	s_sleep 1
	s_add_i32 s98, s98, 1
	s_cmp_lt_u32 s98, 0x40000
	s_cbranch_scc1 .Lxb6_poll

; __device__ __forceinline__ void xcd_barrier(const XcdBarrier& b) {
;     asm volatile("s_waitcnt vmcnt(0)" ::: "memory");
;     __syncthreads();
;     if (threadIdx.x == 0) {
.LBB0_1181:
	s_waitcnt vmcnt(0)
	s_barrier
	v_readfirstlane_b32 s98, v222
	s_nop 3
	s_lshr_b32 s98, s98, 6
	s_cmp_eq_u32 s98, 1
	s_cbranch_scc0 .Lxbi7_skip
	buffer_inv sc1
	s_waitcnt vmcnt(0)

; __device__ __forceinline__ unsigned xb_ld(unsigned* p)              { return __hip_atomic_load(p, __ATOMIC_RELAXED, __HIP_MEMORY_SCOPE_AGENT); }
; __device__ __forceinline__ unsigned xb_add(unsigned* p, unsigned v) { return __hip_atomic_fetch_add(p, v, __ATOMIC_RELAXED, __HIP_MEMORY_SCOPE_AGENT); }
; #define XB_SPIN(cond, bar) do { unsigned _sp = 0; while (cond) { __builtin_amdgcn_s_sleep(1); \
;     if ((++_sp & 255u) == 0u) { if (xb_ld(&(bar)[XB_TMO])) break; if (_sp > XB_SPIN_CAP) { atomicAdd(&(bar)[XB_TMO], 1u); break; } } } } while (0)
; __device__ __forceinline__ void xcd_barrier(const XcdBarrier& b) {
;     ...
;         const unsigned old = xb_add(&bar[XB_XSUB(b.x)], 1u);
;         const unsigned gen = old / nloc;
;         if (old + 1u == (gen + 1u) * nloc) {
;             __builtin_amdgcn_fence(__ATOMIC_RELEASE, "agent");
;             asm volatile("s_waitcnt vmcnt(0)" ::: "memory");
;             const unsigned og = xb_add(&bar[XB_TOP], 1u);
;             const unsigned tg = og / nx;
;             if (og + 1u == (tg + 1u) * nx) xb_add(&bar[XB_TOPGEN], 1u);
;             else XB_SPIN(xb_ld(&bar[XB_TOPGEN]) == tg, bar);
;             __builtin_amdgcn_fence(__ATOMIC_ACQUIRE, "agent");
;             xb_add(&bar[XB_XGEN(b.x)], 1u);
;             asm volatile("s_waitcnt vmcnt(0)" ::: "memory");
;         } else {
;             XB_SPIN(xb_ld(&bar[XB_XGEN(b.x)]) == gen, bar);
;             __builtin_amdgcn_fence(__ATOMIC_ACQUIRE, "agent");
;             asm volatile("s_waitcnt vmcnt(0)" ::: "memory");
.LBB0_1197:
	v_readlane_b32 s2, v254, 59
	v_readlane_b32 s3, v254, 60
	v_readlane_b32 s12, v254, 41
	v_readlane_b32 s13, v254, 42
	s_waitcnt lgkmcnt(0)
	v_mov_b32_e32 v0, s2
	v_mov_b32_e32 v4, s3
	ds_read_b32 v3, v0
	ds_read_b32 v2, v4
	v_mov_b32_e32 v5, 0
	v_mov_b32_e32 v6, 1
	s_nop 1
	global_atomic_add v6, v5, v6, s[12:13] sc0
	v_readlane_b32 s2, v254, 45
	v_readlane_b32 s3, v254, 46
	s_waitcnt vmcnt(0) lgkmcnt(0)
	v_cvt_f32_u32_e32 v0, v3
	v_sub_u32_e32 v4, 0, v3
	v_rcp_iflag_f32_e32 v0, v0
	s_nop 0
	v_mul_f32_e32 v0, 0x4f7ffffe, v0
	v_cvt_u32_f32_e32 v0, v0
	v_mul_lo_u32 v4, v4, v0
	v_mul_hi_u32 v4, v0, v4
	v_add_u32_e32 v0, v0, v4
	v_mul_hi_u32 v0, v6, v0
	v_mul_lo_u32 v4, v0, v3
	v_sub_u32_e32 v4, v6, v4
	v_add_u32_e32 v7, 1, v0
	v_cmp_ge_u32_e32 vcc, v4, v3
	s_nop 1
	v_cndmask_b32_e32 v0, v0, v7, vcc
	v_sub_u32_e32 v7, v4, v3
	v_cndmask_b32_e32 v4, v4, v7, vcc
	v_add_u32_e32 v7, 1, v0
	v_cmp_ge_u32_e32 vcc, v4, v3
	s_nop 1
	v_cndmask_b32_e32 v0, v0, v7, vcc
	v_add_u32_e32 v7, 1, v0
	v_mul_lo_u32 v4, v7, v3
	v_mul_lo_u32 v7, v7, v2
	v_add_u32_e32 v6, 1, v6
	v_cmp_ne_u32_e32 vcc, v6, v4
	s_mov_b32 s98, 0
	s_cbranch_vccnz .Lxb7_early
	s_nop 0
	buffer_wbl2 sc1
	s_waitcnt vmcnt(0)
	v_mov_b32_e32 v6, 1
	global_atomic_add v5, v6, s[2:3]
	s_branch .Lxb7_early
.Lxb7_early:
	s_nop 0
.Lxb7_poll:
	global_load_dword v6, v5, s[2:3] sc1
	s_waitcnt vmcnt(0)
	v_cmp_lt_u32_e32 vcc, v6, v7
	s_cbranch_vccz .Lxb7_done
	s_sleep 1
	s_add_i32 s98, s98, 1
	s_cmp_lt_u32 s98, 0x40000
	s_cbranch_scc1 .Lxb7_poll

; __device__ __forceinline__ unsigned xb_ld(unsigned* p)              { return __hip_atomic_load(p, __ATOMIC_RELAXED, __HIP_MEMORY_SCOPE_AGENT); }
; __device__ __forceinline__ unsigned xb_add(unsigned* p, unsigned v) { return __hip_atomic_fetch_add(p, v, __ATOMIC_RELAXED, __HIP_MEMORY_SCOPE_AGENT); }
; #define XB_SPIN(cond, bar) do { unsigned _sp = 0; while (cond) { __builtin_amdgcn_s_sleep(1); \
;     if ((++_sp & 255u) == 0u) { if (xb_ld(&(bar)[XB_TMO])) break; if (_sp > XB_SPIN_CAP) { atomicAdd(&(bar)[XB_TMO], 1u); break; } } } } while (0)
; __device__ __forceinline__ void xcd_barrier(const XcdBarrier& b) {
;     ...
;         const unsigned old = xb_add(&bar[XB_XSUB(b.x)], 1u);
;         const unsigned gen = old / nloc;
;         if (old + 1u == (gen + 1u) * nloc) {
;             __builtin_amdgcn_fence(__ATOMIC_RELEASE, "agent");
;             asm volatile("s_waitcnt vmcnt(0)" ::: "memory");
;             const unsigned og = xb_add(&bar[XB_TOP], 1u);
;             const unsigned tg = og / nx;
;             if (og + 1u == (tg + 1u) * nx) xb_add(&bar[XB_TOPGEN], 1u);
;             else XB_SPIN(xb_ld(&bar[XB_TOPGEN]) == tg, bar);
;             __builtin_amdgcn_fence(__ATOMIC_ACQUIRE, "agent");
;             xb_add(&bar[XB_XGEN(b.x)], 1u);
;             asm volatile("s_waitcnt vmcnt(0)" ::: "memory");
;         } else {
;             XB_SPIN(xb_ld(&bar[XB_XGEN(b.x)]) == gen, bar);
;             __builtin_amdgcn_fence(__ATOMIC_ACQUIRE, "agent");
;             asm volatile("s_waitcnt vmcnt(0)" ::: "memory");
.LBB0_1291:
	v_readlane_b32 s2, v254, 59
	v_readlane_b32 s3, v254, 60
	v_readlane_b32 s12, v254, 41
	v_readlane_b32 s13, v254, 42
	s_waitcnt lgkmcnt(0)
	v_mov_b32_e32 v0, s2
	v_mov_b32_e32 v4, s3
	ds_read_b32 v3, v0
	ds_read_b32 v2, v4
	v_mov_b32_e32 v5, 0
	v_mov_b32_e32 v6, 1
	s_nop 1
	global_atomic_add v6, v5, v6, s[12:13] sc0
	v_readlane_b32 s2, v254, 45
	v_readlane_b32 s3, v254, 46
	s_waitcnt vmcnt(0) lgkmcnt(0)
	v_cvt_f32_u32_e32 v0, v3
	v_sub_u32_e32 v4, 0, v3
	v_rcp_iflag_f32_e32 v0, v0
	s_nop 0
	v_mul_f32_e32 v0, 0x4f7ffffe, v0
	v_cvt_u32_f32_e32 v0, v0
	v_mul_lo_u32 v4, v4, v0
	v_mul_hi_u32 v4, v0, v4
	v_add_u32_e32 v0, v0, v4
	v_mul_hi_u32 v0, v6, v0
	v_mul_lo_u32 v4, v0, v3
	v_sub_u32_e32 v4, v6, v4
	v_add_u32_e32 v7, 1, v0
	v_cmp_ge_u32_e32 vcc, v4, v3
	s_nop 1
	v_cndmask_b32_e32 v0, v0, v7, vcc
	v_sub_u32_e32 v7, v4, v3
	v_cndmask_b32_e32 v4, v4, v7, vcc
	v_add_u32_e32 v7, 1, v0
	v_cmp_ge_u32_e32 vcc, v4, v3
	s_nop 1
	v_cndmask_b32_e32 v0, v0, v7, vcc
	v_add_u32_e32 v7, 1, v0
	v_mul_lo_u32 v4, v7, v3
	v_mul_lo_u32 v7, v7, v2
	v_add_u32_e32 v6, 1, v6
	v_cmp_ne_u32_e32 vcc, v6, v4
	s_mov_b32 s98, 0
	s_cbranch_vccnz .Lxb8_early
	s_nop 0
	buffer_wbl2 sc1
	s_waitcnt vmcnt(0)
	v_mov_b32_e32 v6, 1
	global_atomic_add v5, v6, s[2:3]
	s_branch .Lxb8_early
.Lxb8_early:
	s_nop 0
.Lxb8_poll:
	global_load_dword v6, v5, s[2:3] sc1
	s_waitcnt vmcnt(0)
	v_cmp_lt_u32_e32 vcc, v6, v7
	s_cbranch_vccz .Lxb8_done
	s_sleep 1
	s_add_i32 s98, s98, 1
	s_cmp_lt_u32 s98, 0x40000
	s_cbranch_scc1 .Lxb8_poll

; __device__ __forceinline__ unsigned xb_ld(unsigned* p)              { return __hip_atomic_load(p, __ATOMIC_RELAXED, __HIP_MEMORY_SCOPE_AGENT); }
; __device__ __forceinline__ unsigned xb_add(unsigned* p, unsigned v) { return __hip_atomic_fetch_add(p, v, __ATOMIC_RELAXED, __HIP_MEMORY_SCOPE_AGENT); }
; #define XB_SPIN(cond, bar) do { unsigned _sp = 0; while (cond) { __builtin_amdgcn_s_sleep(1); \
;     if ((++_sp & 255u) == 0u) { if (xb_ld(&(bar)[XB_TMO])) break; if (_sp > XB_SPIN_CAP) { atomicAdd(&(bar)[XB_TMO], 1u); break; } } } } while (0)
; __device__ __forceinline__ void xcd_barrier(const XcdBarrier& b) {
;     ...
;         const unsigned old = xb_add(&bar[XB_XSUB(b.x)], 1u);
;         const unsigned gen = old / nloc;
;         if (old + 1u == (gen + 1u) * nloc) {
;             __builtin_amdgcn_fence(__ATOMIC_RELEASE, "agent");
;             asm volatile("s_waitcnt vmcnt(0)" ::: "memory");
;             const unsigned og = xb_add(&bar[XB_TOP], 1u);
;             const unsigned tg = og / nx;
;             if (og + 1u == (tg + 1u) * nx) xb_add(&bar[XB_TOPGEN], 1u);
;             else XB_SPIN(xb_ld(&bar[XB_TOPGEN]) == tg, bar);
;             __builtin_amdgcn_fence(__ATOMIC_ACQUIRE, "agent");
;             xb_add(&bar[XB_XGEN(b.x)], 1u);
;             asm volatile("s_waitcnt vmcnt(0)" ::: "memory");
;         } else {
;             XB_SPIN(xb_ld(&bar[XB_XGEN(b.x)]) == gen, bar);
;             __builtin_amdgcn_fence(__ATOMIC_ACQUIRE, "agent");
;             asm volatile("s_waitcnt vmcnt(0)" ::: "memory");
.LBB0_1367:
	v_readlane_b32 s2, v254, 59
	v_readlane_b32 s3, v254, 60
	v_readlane_b32 s12, v254, 41
	v_readlane_b32 s13, v254, 42
	s_waitcnt lgkmcnt(0)
	v_mov_b32_e32 v0, s2
	v_mov_b32_e32 v4, s3
	ds_read_b32 v3, v0
	ds_read_b32 v2, v4
	v_mov_b32_e32 v5, 0
	v_mov_b32_e32 v6, 1
	s_nop 1
	global_atomic_add v6, v5, v6, s[12:13] sc0
	v_readlane_b32 s2, v254, 45
	v_readlane_b32 s3, v254, 46
	s_waitcnt vmcnt(0) lgkmcnt(0)
	v_cvt_f32_u32_e32 v0, v3
	v_sub_u32_e32 v4, 0, v3
	v_rcp_iflag_f32_e32 v0, v0
	s_nop 0
	v_mul_f32_e32 v0, 0x4f7ffffe, v0
	v_cvt_u32_f32_e32 v0, v0
	v_mul_lo_u32 v4, v4, v0
	v_mul_hi_u32 v4, v0, v4
	v_add_u32_e32 v0, v0, v4
	v_mul_hi_u32 v0, v6, v0
	v_mul_lo_u32 v4, v0, v3
	v_sub_u32_e32 v4, v6, v4
	v_add_u32_e32 v7, 1, v0
	v_cmp_ge_u32_e32 vcc, v4, v3
	s_nop 1
	v_cndmask_b32_e32 v0, v0, v7, vcc
	v_sub_u32_e32 v7, v4, v3
	v_cndmask_b32_e32 v4, v4, v7, vcc
	v_add_u32_e32 v7, 1, v0
	v_cmp_ge_u32_e32 vcc, v4, v3
	s_nop 1
	v_cndmask_b32_e32 v0, v0, v7, vcc
	v_add_u32_e32 v7, 1, v0
	v_mul_lo_u32 v4, v7, v3
	v_mul_lo_u32 v7, v7, v2
	v_add_u32_e32 v6, 1, v6
	v_cmp_ne_u32_e32 vcc, v6, v4
	s_mov_b32 s98, 0
	s_cbranch_vccnz .Lxb9_early
	s_nop 0
	buffer_wbl2 sc1
	s_waitcnt vmcnt(0)
	v_mov_b32_e32 v6, 1
	global_atomic_add v5, v6, s[2:3]
	s_branch .Lxb9_early
.Lxb9_early:
	s_nop 0
.Lxb9_poll:
	global_load_dword v6, v5, s[2:3] sc1
	s_waitcnt vmcnt(0)
	v_cmp_lt_u32_e32 vcc, v6, v7
	s_cbranch_vccz .Lxb9_done
	s_sleep 1
	s_add_i32 s98, s98, 1
	s_cmp_lt_u32 s98, 0x40000
	s_cbranch_scc1 .Lxb9_poll

; __device__ __forceinline__ void xcd_barrier(const XcdBarrier& b) {
;     ...
;     if (threadIdx.x == 0) {
;         unsigned* bar = b.bar;
;         __builtin_amdgcn_s_waitcnt(0);
;         unsigned nloc = b.st[0], nx = b.st[1];
;         if (nloc == 0u) { xcd_barrier_complete(bar, b.x, nloc, nx); b.st[0] = nloc; b.st[1] = nx; }
.Lxbi10_skip:
	s_mov_b64 s[8:9], exec
	v_readlane_b32 s2, v254, 0
	v_readlane_b32 s3, v254, 1
	s_and_b64 s[2:3], s[8:9], s[2:3]
	v_readlane_b32 s14, v255, 17
	s_mov_b64 exec, s[2:3]
	s_cbranch_execnz .LBB0_1446
	s_getpc_b64 s[98:99]

; __device__ __forceinline__ unsigned xb_ld(unsigned* p)              { return __hip_atomic_load(p, __ATOMIC_RELAXED, __HIP_MEMORY_SCOPE_AGENT); }
; __device__ __forceinline__ unsigned xb_add(unsigned* p, unsigned v) { return __hip_atomic_fetch_add(p, v, __ATOMIC_RELAXED, __HIP_MEMORY_SCOPE_AGENT); }
; #define XB_SPIN(cond, bar) do { unsigned _sp = 0; while (cond) { __builtin_amdgcn_s_sleep(1); \
;     if ((++_sp & 255u) == 0u) { if (xb_ld(&(bar)[XB_TMO])) break; if (_sp > XB_SPIN_CAP) { atomicAdd(&(bar)[XB_TMO], 1u); break; } } } } while (0)
; __device__ __forceinline__ void xcd_barrier(const XcdBarrier& b) {
;     ...
;         const unsigned old = xb_add(&bar[XB_XSUB(b.x)], 1u);
;         const unsigned gen = old / nloc;
;         if (old + 1u == (gen + 1u) * nloc) {
;             __builtin_amdgcn_fence(__ATOMIC_RELEASE, "agent");
;             asm volatile("s_waitcnt vmcnt(0)" ::: "memory");
;             const unsigned og = xb_add(&bar[XB_TOP], 1u);
;             const unsigned tg = og / nx;
;             if (og + 1u == (tg + 1u) * nx) xb_add(&bar[XB_TOPGEN], 1u);
;             else XB_SPIN(xb_ld(&bar[XB_TOPGEN]) == tg, bar);
;             __builtin_amdgcn_fence(__ATOMIC_ACQUIRE, "agent");
;             xb_add(&bar[XB_XGEN(b.x)], 1u);
;             asm volatile("s_waitcnt vmcnt(0)" ::: "memory");
;         } else {
;             XB_SPIN(xb_ld(&bar[XB_XGEN(b.x)]) == gen, bar);
;             __builtin_amdgcn_fence(__ATOMIC_ACQUIRE, "agent");
;             asm volatile("s_waitcnt vmcnt(0)" ::: "memory");
.LBB0_1461:
	v_readlane_b32 s2, v254, 59
	v_readlane_b32 s3, v254, 60
	v_readlane_b32 s12, v254, 41
	v_readlane_b32 s13, v254, 42
	s_waitcnt lgkmcnt(0)
	v_mov_b32_e32 v0, s2
	v_mov_b32_e32 v4, s3
	ds_read_b32 v3, v0
	ds_read_b32 v2, v4
	v_mov_b32_e32 v5, 0
	v_mov_b32_e32 v6, 1
	s_nop 1
	global_atomic_add v6, v5, v6, s[12:13] sc0
	v_readlane_b32 s2, v254, 45
	v_readlane_b32 s3, v254, 46
	s_waitcnt vmcnt(0) lgkmcnt(0)
	v_cvt_f32_u32_e32 v0, v3
	v_sub_u32_e32 v4, 0, v3
	v_rcp_iflag_f32_e32 v0, v0
	s_nop 0
	v_mul_f32_e32 v0, 0x4f7ffffe, v0
	v_cvt_u32_f32_e32 v0, v0
	v_mul_lo_u32 v4, v4, v0
	v_mul_hi_u32 v4, v0, v4
	v_add_u32_e32 v0, v0, v4
	v_mul_hi_u32 v0, v6, v0
	v_mul_lo_u32 v4, v0, v3
	v_sub_u32_e32 v4, v6, v4
	v_add_u32_e32 v7, 1, v0
	v_cmp_ge_u32_e32 vcc, v4, v3
	s_nop 1
	v_cndmask_b32_e32 v0, v0, v7, vcc
	v_sub_u32_e32 v7, v4, v3
	v_cndmask_b32_e32 v4, v4, v7, vcc
	v_add_u32_e32 v7, 1, v0
	v_cmp_ge_u32_e32 vcc, v4, v3
	s_nop 1
	v_cndmask_b32_e32 v0, v0, v7, vcc
	v_add_u32_e32 v7, 1, v0
	v_mul_lo_u32 v4, v7, v3
	v_mul_lo_u32 v7, v7, v2
	v_add_u32_e32 v6, 1, v6
	v_cmp_ne_u32_e32 vcc, v6, v4
	s_mov_b32 s98, 0
	s_cbranch_vccnz .Lxb10_early
	s_nop 0
	buffer_wbl2 sc1
	s_waitcnt vmcnt(0)
	v_mov_b32_e32 v6, 1
	global_atomic_add v5, v6, s[2:3]
	s_branch .Lxb10_early
.Lxb10_early:
	s_nop 0
.Lxb10_poll:
	global_load_dword v6, v5, s[2:3] sc1
	s_waitcnt vmcnt(0)
	v_cmp_lt_u32_e32 vcc, v6, v7
	s_cbranch_vccz .Lxb10_done
	s_sleep 1
	s_add_i32 s98, s98, 1
	s_cmp_lt_u32 s98, 0x40000
	s_cbranch_scc1 .Lxb10_poll
